# half-workgroup conversion streams, second half of each workgroup starts half an item late (alternating load / quantise)
# speedup vs baseline: 1.0073x; 1.0073x over previous
.Lp0_after_colmax:
	v_readlane_b32 s0, v254, 15
	s_lshl_b32 s21, s0, 9
	s_mov_b32 s14, s90
	s_cmpk_gt_i32 s90, 0x69ff
	s_waitcnt lgkmcnt(0)
	s_barrier
	s_cbranch_scc1 .LBB0_115
	v_mbcnt_lo_u32_b32 v135, -1, 0
	v_mbcnt_hi_u32_b32 v135, -1, v135
	v_lshrrev_b32_e32 v136, 3, v135
	v_and_b32_e32 v137, 7, v135
	v_lshlrev_b32_e32 v230, 4, v137
	v_lshlrev_b32_e32 v195, 5, v137
	v_lshlrev_b32_e32 v231, 15, v137
	v_lshl_add_u32 v231, v136, 3, v231
	v_readlane_b32 s62, v254, 17
	v_readlane_b32 s1, v254, 16
	v_readlane_b32 s72, v254, 15
	s_mov_b32 s74, 0x42fe0000
	s_mov_b32 s11, 0
	s_and_b32 s12, s72, 3
	s_lshr_b32 s72, s72, 2
	s_and_b32 s15, s1, 3
	s_lshr_b32 s3, s1, 2
	s_lshl_b32 s72, s72, 1
	s_add_u32 s72, s72, s3
	s_lshl_b32 s17, s3, 11
	s_add_u32 s17, s17, 0x21000
	s_lshl_b32 s3, s3, 4
	s_add_u32 s3, s3, 0x22000
	v_mov_b32_e32 v250, s3
	v_mov_b32_e32 v251, 0
	ds_write_b32 v250, v251
	v_mov_b32_e32 v251, 1
	v_and_b32_e32 v252, 31, v135
	v_lshlrev_b32_e32 v252, 5, v252
	s_mov_b32 s16, 0
	s_mov_b32 s53, 0
	s_lshl_b32 s52, s12, 10
	s_lshl_b32 s3, s15, 8
	s_add_u32 s52, s52, s3
	s_lshl_b32 s3, s72, 11
	s_add_u32 s3, s3, 0x8000
	s_cmp_ge_u32 s72, 112
	s_cselect_b32 s10, 0x48000, 0
	s_add_u32 s3, s3, s10
	s_add_u32 s50, s34, s3
	s_addc_u32 s51, s35, 0
	s_waitcnt lgkmcnt(0)
	s_barrier
	s_cmp_lt_u32 s1, 4
	s_cbranch_scc1 .Lc32_nodelay_0
	s_sleep 127
.Lc32_nodelay_0:
	v_lshlrev_b32_e32 v139, 10, v137
	v_lshl_add_u32 v139, v136, 2, v139
	v_add_u32_e32 v139, s62, v139
	v_lshlrev_b32_e32 v174, 2, v135
	v_xor_b32_e32 v192, 0x20, v174
	v_xor_b32_e32 v193, 0x40, v174
	v_xor_b32_e32 v194, 0x80, v174
	v_lshrrev_b32_e32 v175, 4, v135
	v_and_b32_e32 v176, 15, v135
	v_lshlrev_b32_e32 v212, 8, v175
	v_lshl_add_u32 v212, v176, 4, v212
	v_add_u32_e32 v212, s62, v212
	v_lshlrev_b32_e32 v213, 12, v175
	v_lshl_add_u32 v213, v176, 4, v213
	v_readlane_b32 s48, v255, 47
	v_readlane_b32 s49, v255, 48
	v_mul_u32_u24_e32 v138, 0x20000, v136
	v_lshl_add_u32 v138, v137, 4, v138
	s_mul_i32 s3, s52, 0x8000
	s_nop 1
	s_add_u32 s48, s48, s3
	s_addc_u32 s49, s49, 0
	s_mov_b32 s0, s72
	s_cmp_ge_u32 s0, 0x100
	s_cbranch_scc1 .Lc32_gates_done
	s_lshl_b32 s3, s0, 7
	s_add_u32 s56, s48, s3
	s_addc_u32 s57, s49, 0
	global_load_dwordx4 v[6:9], v138, s[56:57]
	s_add_u32 s56, s56, 0x8000
	s_addc_u32 s57, s57, 0
	global_load_dwordx4 v[10:13], v138, s[56:57]
	s_add_u32 s56, s56, 0x8000
	s_addc_u32 s57, s57, 0
	global_load_dwordx4 v[14:17], v138, s[56:57]
	s_add_u32 s56, s56, 0x8000
	s_addc_u32 s57, s57, 0
	global_load_dwordx4 v[18:21], v138, s[56:57]
	s_add_u32 s56, s56, 0xe8000
	s_addc_u32 s57, s57, 0
	global_load_dwordx4 v[22:25], v138, s[56:57]
	s_add_u32 s56, s56, 0x8000
	s_addc_u32 s57, s57, 0
	global_load_dwordx4 v[26:29], v138, s[56:57]
	s_add_u32 s56, s56, 0x8000
	s_addc_u32 s57, s57, 0
	global_load_dwordx4 v[30:33], v138, s[56:57]
	s_add_u32 s56, s56, 0x8000
	s_addc_u32 s57, s57, 0
	global_load_dwordx4 v[34:37], v138, s[56:57]
	s_add_u32 s56, s56, 0xe8000
	s_addc_u32 s57, s57, 0
	global_load_dwordx4 v[38:41], v138, s[56:57]
	s_add_u32 s56, s56, 0x8000
	s_addc_u32 s57, s57, 0
	global_load_dwordx4 v[42:45], v138, s[56:57]
	s_add_u32 s56, s56, 0x8000
	s_addc_u32 s57, s57, 0
	global_load_dwordx4 v[46:49], v138, s[56:57]
	s_add_u32 s56, s56, 0x8000
	s_addc_u32 s57, s57, 0
	global_load_dwordx4 v[50:53], v138, s[56:57]
	s_add_u32 s56, s56, 0xe8000
	s_addc_u32 s57, s57, 0
	global_load_dwordx4 v[54:57], v138, s[56:57]
	s_add_u32 s56, s56, 0x8000
	s_addc_u32 s57, s57, 0
	global_load_dwordx4 v[58:61], v138, s[56:57]
	s_add_u32 s56, s56, 0x8000
	s_addc_u32 s57, s57, 0
	global_load_dwordx4 v[62:65], v138, s[56:57]
	s_add_u32 s56, s56, 0x8000
	s_addc_u32 s57, s57, 0
	global_load_dwordx4 v[66:69], v138, s[56:57]
	s_add_u32 s56, s56, 0xe8000
	s_addc_u32 s57, s57, 0
	global_load_dwordx4 v[70:73], v138, s[56:57]
	s_add_u32 s56, s56, 0x8000
	s_addc_u32 s57, s57, 0
	global_load_dwordx4 v[74:77], v138, s[56:57]
	s_add_u32 s56, s56, 0x8000
	s_addc_u32 s57, s57, 0
	global_load_dwordx4 v[78:81], v138, s[56:57]
	s_add_u32 s56, s56, 0x8000
	s_addc_u32 s57, s57, 0
	global_load_dwordx4 v[82:85], v138, s[56:57]
	s_add_u32 s56, s56, 0xe8000
	s_addc_u32 s57, s57, 0
	global_load_dwordx4 v[86:89], v138, s[56:57]
	s_add_u32 s56, s56, 0x8000
	s_addc_u32 s57, s57, 0
	global_load_dwordx4 v[90:93], v138, s[56:57]
	s_add_u32 s56, s56, 0x8000
	s_addc_u32 s57, s57, 0
	global_load_dwordx4 v[94:97], v138, s[56:57]
	s_add_u32 s56, s56, 0x8000
	s_addc_u32 s57, s57, 0
	global_load_dwordx4 v[98:101], v138, s[56:57]
	s_add_u32 s56, s56, 0xe8000
	s_addc_u32 s57, s57, 0
	global_load_dwordx4 v[102:105], v138, s[56:57]
	s_add_u32 s56, s56, 0x8000
	s_addc_u32 s57, s57, 0
	global_load_dwordx4 v[106:109], v138, s[56:57]
	s_add_u32 s56, s56, 0x8000
	s_addc_u32 s57, s57, 0
	global_load_dwordx4 v[110:113], v138, s[56:57]
	s_add_u32 s56, s56, 0x8000
	s_addc_u32 s57, s57, 0
	global_load_dwordx4 v[114:117], v138, s[56:57]
	s_add_u32 s56, s56, 0xe8000
	s_addc_u32 s57, s57, 0
	global_load_dwordx4 v[118:121], v138, s[56:57]
	s_add_u32 s56, s56, 0x8000
	s_addc_u32 s57, s57, 0
	global_load_dwordx4 v[122:125], v138, s[56:57]
	s_add_u32 s56, s56, 0x8000
	s_addc_u32 s57, s57, 0
	global_load_dwordx4 v[126:129], v138, s[56:57]
	s_add_u32 s56, s56, 0x8000
	s_addc_u32 s57, s57, 0
	global_load_dwordx4 v[130:133], v138, s[56:57]

.LBB0_484:
	v_mbcnt_lo_u32_b32 v135, -1, 0
	v_mbcnt_hi_u32_b32 v135, -1, v135
	v_lshrrev_b32_e32 v136, 3, v135
	v_and_b32_e32 v137, 7, v135
	v_lshlrev_b32_e32 v230, 4, v137
	v_lshlrev_b32_e32 v195, 5, v137
	v_lshlrev_b32_e32 v231, 15, v137
	v_lshl_add_u32 v231, v136, 3, v231
	v_readlane_b32 s7, v254, 17
	v_readlane_b32 s1, v254, 16
	v_readlane_b32 s13, v254, 15
	s_mov_b32 s11, 0x42fe0000
	s_mov_b32 s5, 0
	s_and_b32 s60, s13, 3
	s_lshr_b32 s13, s13, 2
	s_and_b32 s15, s1, 3
	s_lshr_b32 s3, s1, 2
	s_lshl_b32 s13, s13, 1
	s_add_u32 s13, s13, s3
	s_lshl_b32 s20, s3, 11
	s_add_u32 s20, s20, 0x21000
	s_lshl_b32 s3, s3, 4
	s_add_u32 s3, s3, 0x22000
	v_mov_b32_e32 v250, s3
	v_mov_b32_e32 v251, 0
	ds_write_b32 v250, v251
	v_mov_b32_e32 v251, 1
	v_and_b32_e32 v252, 31, v135
	v_lshlrev_b32_e32 v252, 5, v252
	s_mov_b32 s17, 0
	s_mov_b32 s61, 64
	s_lshl_b32 s64, s60, 10
	s_lshl_b32 s3, s15, 8
	s_add_u32 s64, s64, s3
	s_lshl_b32 s3, s13, 11
	s_add_u32 s3, s3, 0x8000
	s_cmp_ge_u32 s13, 112
	s_cselect_b32 s4, 0x48000, 0
	s_add_u32 s3, s3, s4
	s_add_u32 s62, s34, s3
	s_addc_u32 s63, s35, 0
	s_waitcnt lgkmcnt(0)
	s_barrier
	s_cmp_lt_u32 s1, 4
	s_cbranch_scc1 .Lc32p3_nodelay_64
	s_sleep 127
.Lc32p3_nodelay_64:
	v_lshlrev_b32_e32 v139, 10, v137
	v_lshl_add_u32 v139, v136, 2, v139
	v_add_u32_e32 v139, s7, v139
	v_lshlrev_b32_e32 v174, 2, v135
	v_xor_b32_e32 v192, 0x20, v174
	v_xor_b32_e32 v193, 0x40, v174
	v_xor_b32_e32 v194, 0x80, v174
	v_lshrrev_b32_e32 v175, 4, v135
	v_and_b32_e32 v176, 15, v135
	v_lshlrev_b32_e32 v212, 8, v175
	v_lshl_add_u32 v212, v176, 4, v212
	v_add_u32_e32 v212, s7, v212
	v_lshlrev_b32_e32 v213, 12, v175
	v_lshl_add_u32 v213, v176, 4, v213
	v_readlane_b32 s52, v255, 61
	v_readlane_b32 s53, v255, 62
	v_mul_u32_u24_e32 v138, 0x56000, v136
	v_lshl_add_u32 v138, v137, 4, v138
	s_mul_i32 s3, s64, 0x15800
	s_nop 1
	s_add_u32 s52, s52, s3
	s_addc_u32 s53, s53, 0
	s_mov_b32 s0, s13
	s_cmp_ge_u32 s0, 0x2b0
	s_cbranch_scc1 .Lc32p3_ffn2_done
	s_lshl_b32 s3, s0, 7
	s_add_u32 s54, s52, s3
	s_addc_u32 s55, s53, 0
	global_load_dwordx4 v[6:9], v138, s[54:55]
	s_add_u32 s54, s54, 0x15800
	s_addc_u32 s55, s55, 0
	global_load_dwordx4 v[10:13], v138, s[54:55]
	s_add_u32 s54, s54, 0x15800
	s_addc_u32 s55, s55, 0
	global_load_dwordx4 v[14:17], v138, s[54:55]
	s_add_u32 s54, s54, 0x15800
	s_addc_u32 s55, s55, 0
	global_load_dwordx4 v[18:21], v138, s[54:55]
	s_add_u32 s54, s54, 0x26f800
	s_addc_u32 s55, s55, 0
	global_load_dwordx4 v[22:25], v138, s[54:55]
	s_add_u32 s54, s54, 0x15800
	s_addc_u32 s55, s55, 0
	global_load_dwordx4 v[26:29], v138, s[54:55]
	s_add_u32 s54, s54, 0x15800
	s_addc_u32 s55, s55, 0
	global_load_dwordx4 v[30:33], v138, s[54:55]
	s_add_u32 s54, s54, 0x15800
	s_addc_u32 s55, s55, 0
	global_load_dwordx4 v[34:37], v138, s[54:55]
	s_add_u32 s54, s54, 0x26f800
	s_addc_u32 s55, s55, 0
	global_load_dwordx4 v[38:41], v138, s[54:55]
	s_add_u32 s54, s54, 0x15800
	s_addc_u32 s55, s55, 0
	global_load_dwordx4 v[42:45], v138, s[54:55]
	s_add_u32 s54, s54, 0x15800
	s_addc_u32 s55, s55, 0
	global_load_dwordx4 v[46:49], v138, s[54:55]
	s_add_u32 s54, s54, 0x15800
	s_addc_u32 s55, s55, 0
	global_load_dwordx4 v[50:53], v138, s[54:55]
	s_add_u32 s54, s54, 0x26f800
	s_addc_u32 s55, s55, 0
	global_load_dwordx4 v[54:57], v138, s[54:55]
	s_add_u32 s54, s54, 0x15800
	s_addc_u32 s55, s55, 0
	global_load_dwordx4 v[58:61], v138, s[54:55]
	s_add_u32 s54, s54, 0x15800
	s_addc_u32 s55, s55, 0
	global_load_dwordx4 v[62:65], v138, s[54:55]
	s_add_u32 s54, s54, 0x15800
	s_addc_u32 s55, s55, 0
	global_load_dwordx4 v[66:69], v138, s[54:55]
	s_add_u32 s54, s54, 0x26f800
	s_addc_u32 s55, s55, 0
	global_load_dwordx4 v[70:73], v138, s[54:55]
	s_add_u32 s54, s54, 0x15800
	s_addc_u32 s55, s55, 0
	global_load_dwordx4 v[74:77], v138, s[54:55]
	s_add_u32 s54, s54, 0x15800
	s_addc_u32 s55, s55, 0
	global_load_dwordx4 v[78:81], v138, s[54:55]
	s_add_u32 s54, s54, 0x15800
	s_addc_u32 s55, s55, 0
	global_load_dwordx4 v[82:85], v138, s[54:55]
	s_add_u32 s54, s54, 0x26f800
	s_addc_u32 s55, s55, 0
	global_load_dwordx4 v[86:89], v138, s[54:55]
	s_add_u32 s54, s54, 0x15800
	s_addc_u32 s55, s55, 0
	global_load_dwordx4 v[90:93], v138, s[54:55]
	s_add_u32 s54, s54, 0x15800
	s_addc_u32 s55, s55, 0
	global_load_dwordx4 v[94:97], v138, s[54:55]
	s_add_u32 s54, s54, 0x15800
	s_addc_u32 s55, s55, 0
	global_load_dwordx4 v[98:101], v138, s[54:55]
	s_add_u32 s54, s54, 0x26f800
	s_addc_u32 s55, s55, 0
	global_load_dwordx4 v[102:105], v138, s[54:55]
	s_add_u32 s54, s54, 0x15800
	s_addc_u32 s55, s55, 0
	global_load_dwordx4 v[106:109], v138, s[54:55]
	s_add_u32 s54, s54, 0x15800
	s_addc_u32 s55, s55, 0
	global_load_dwordx4 v[110:113], v138, s[54:55]
	s_add_u32 s54, s54, 0x15800
	s_addc_u32 s55, s55, 0
	global_load_dwordx4 v[114:117], v138, s[54:55]
	s_add_u32 s54, s54, 0x26f800
	s_addc_u32 s55, s55, 0
	global_load_dwordx4 v[118:121], v138, s[54:55]
	s_add_u32 s54, s54, 0x15800
	s_addc_u32 s55, s55, 0
	global_load_dwordx4 v[122:125], v138, s[54:55]
	s_add_u32 s54, s54, 0x15800
	s_addc_u32 s55, s55, 0
	global_load_dwordx4 v[126:129], v138, s[54:55]
	s_add_u32 s54, s54, 0x15800
	s_addc_u32 s55, s55, 0
	global_load_dwordx4 v[130:133], v138, s[54:55]
